# attention tile top: vmcnt(1) before the K tile LDS write, vmcnt(0) only before the V tile LDS write
# baseline (speedup 1.0000x reference)
; #define LAS __attribute__((address_space(3)))
; __device__ __forceinline__ void attn_unit(LAS unsigned char* lds, const bf16_t* Q, const bf16_t* Kb, const bf16_t* Vb, bf16_t* O, const float* sink,
;                                           int qrow0, int kvh, int crow0, int lrow0, int jlo, int jhi, int qpos0, const int wave_s) {
;     ...
;     for (int ti = 0; ti < ntile; ++ti) {
;         asm volatile(".p2align 4\n\ts_nop 0" ::: "memory");
;         LAS unsigned char* kb = lds + ATT_K + (ti & 1) * 64 * KSTR; LAS unsigned char* vb = lds + ATT_V + (ti & 1) * 64 * VSTR;
;         *(LAS u32x4*)(kb + skey * KSTR + sch * 16) = kreg; *(LAS u32x4*)(vb + skey * VSTR + sch * 16) = vreg;
;         __syncthreads();
;         if (ti + 1 < ntile) { const int tn = ti + 1; const int rb = tn < 4 ? crow0 + 64 * tn : lrow0 + 64 * (jlo + tn - 4);
;             kreg = *(const u32x4*)(Kb + (size_t)(rb + skey) * 256 + gcol); vreg = *(const u32x4*)(Vb + (size_t)(rb + skey) * 256 + gcol); }
.LBB0_347:
	s_and_b32 s8, s2, 64
	s_mul_i32 s9, s8, 0x90
	s_add_i32 s34, s9, 0
	s_mul_i32 s8, s8, 48
	s_add_i32 s31, s34, s8
	s_add_i32 s29, s30, 1
	.p2align 4
	s_nop 0
	s_cmp_ge_u32 s29, s21
	v_add3_u32 v64, s34, v193, v192
	s_cselect_b64 s[8:9], -1, 0
	s_waitcnt vmcnt(1)
	ds_write_b128 v64, v[132:135]
	v_add3_u32 v64, s31, v194, v192
	s_and_b64 vcc, exec, s[8:9]
	s_waitcnt vmcnt(0)
	ds_write_b128 v64, v[128:131] offset:18432
	s_waitcnt lgkmcnt(0)
	s_cbranch_vccnz .LBB0_353
	s_cmp_gt_u32 s30, 2
	s_mov_b64 s[12:13], -1
	s_cbranch_scc0 .LBB0_350
	s_add_i32 s12, s29, s20
	s_lshl_b32 s12, s12, 6
	s_add_i32 s35, s26, s12
	s_mov_b64 s[12:13], 0
